# P2 per-token loads issued together with hoisted gains; P5 QK K-fragment double buffering; P11 final-norm gains hoisted out of token loop
# speedup vs baseline: 1.0924x; 1.0086x over previous
; __device__ void phase_small(const Params& p) {
;   char* ws = p.ws;
;   const int gw = (blockIdx.x * 256 + threadIdx.x) >> 6, nw = (gridDim.x * 256) >> 6, lane = threadIdx.x & 63;
;   const float* zcq = (const float*)(ws + F_ZCQ); const float* zckv = (const float*)(ws + F_ZCKV); const float* zkr = (const float*)(ws + F_ZKR);
;   bf16_t* cq = (bf16_t*)(ws + F_CQ); bf16_t* ckva = (bf16_t*)(ws + W_G); bf16_t* kpea = (bf16_t*)(ws + W_KPE);
;   const float2* rt = (const float2*)(ws + W_ROPE);
;   for (int t = gw; t < T; t += nw) {
;     {
;       f32x4 v = *(const f32x4*)(zcq + (size_t)t * 256 + lane * 4);
;       float ss = wave_sum(v[0] * v[0] + v[1] * v[1] + v[2] * v[2] + v[3] * v[3]);
;       const float rs = rsqrtf(ss * (1.f / 256.f) + EPS);
;       f32x4 g = *(const f32x4*)(p.in[11] + lane * 4);
;     ...
;       float2 g = *(const float2*)(p.in[13] + lane * 2);
.LBB0_346:
	s_mov_b64 s[46:47], exec
	v_readlane_b32 s0, v248, 56
	v_readlane_b32 s1, v248, 57
	s_and_b64 s[0:1], s[46:47], s[0:1]
	s_mov_b64 exec, s[0:1]
	s_cbranch_execz .LBB0_355
	v_cmp_lt_i32_e32 vcc, v52, v51
	s_mov_b64 s[48:49], 0
	v_mov_b64_e32 v[32:33], v[22:23]
	v_cndmask_b32_e32 v2, v50, v52, vcc
	v_cmp_lt_i32_e32 vcc, v53, v51
	v_lshlrev_b32_e32 v29, 2, v2
	v_mov_b64_e32 v[34:35], v[20:21]
	v_cndmask_b32_e32 v2, v50, v53, vcc
	v_cmp_lt_i32_e32 vcc, v54, v51
	v_lshlrev_b32_e32 v31, 2, v2
	v_mov_b64_e32 v[36:37], v[18:19]
	v_cndmask_b32_e32 v2, v50, v54, vcc
	v_cmp_lt_i32_e32 vcc, v55, v51
	v_lshlrev_b32_e32 v59, 2, v2
	v_mov_b64_e32 v[38:39], v[16:17]
	v_cndmask_b32_e32 v2, v50, v55, vcc
	v_cmp_lt_i32_e32 vcc, v56, v51
	v_lshlrev_b32_e32 v60, 2, v2
	v_mov_b64_e32 v[40:41], v[14:15]
	v_cndmask_b32_e32 v2, v50, v56, vcc
	v_cmp_lt_i32_e32 vcc, v57, v51
	v_lshlrev_b32_e32 v61, 2, v2
	v_mov_b64_e32 v[42:43], v[12:13]
	v_cndmask_b32_e32 v2, v50, v57, vcc
	v_lshlrev_b32_e32 v62, 2, v2
	v_mov_b64_e32 v[44:45], v[0:1]
	v_mov_b32_e32 v63, v0
	global_load_dwordx4 v[100:103], v[8:9], off
	global_load_dwordx2 v[104:105], v[10:11], off
	s_branch .LBB0_349

; __device__ __forceinline__ unsigned pk2(float lo, float hi) { f32v2_t v = {lo, hi}; bf16v2_t r = __builtin_convertvector(v, bf16v2_t); return __builtin_bit_cast(unsigned, r); }
; __device__ __forceinline__ bf16_t f2bf(float x) { return (bf16_t)(pk2(x, 0.f) & 0xffffu); }
; __device__ void phase_small(const Params& p) {
;     ...
;   for (int t = gw; t < T; t += nw) {
;     {
;       f32x4 v = *(const f32x4*)(zcq + (size_t)t * 256 + lane * 4);
;       float ss = wave_sum(v[0] * v[0] + v[1] * v[1] + v[2] * v[2] + v[3] * v[3]);
;       const float rs = rsqrtf(ss * (1.f / 256.f) + EPS);
;       f32x4 g = *(const f32x4*)(p.in[11] + lane * 4);
;       u32x2 w; w.x = pk2(v[0] * rs * g[0], v[1] * rs * g[1]); w.y = pk2(v[2] * rs * g[2], v[3] * rs * g[3]);
;       *(u32x2*)(cq + (size_t)t * LDQ + lane * 4) = w;
;     }
;     const int kr = keyrow_of_token(t);
;     {
;       float2 v = *(const float2*)(zckv + (size_t)t * 128 + lane * 2);
;       float ss = wave_sum(v.x * v.x + v.y * v.y);
;       const float rs = rsqrtf(ss * (1.f / 128.f) + EPS);
;       float2 g = *(const float2*)(p.in[13] + lane * 2);
;       const float a = v.x * rs * g.x, b = v.y * rs * g.y;
;       float* o = (t < TP) ? p.out + O_CP + (size_t)t * 128 : p.out + O_CS + (size_t)(t - TP) * 128;
;       *(float2*)(o + lane * 2) = make_float2(a, b);
;       *(unsigned*)(ckva + (size_t)kr * LDK + lane * 2) = pk2(a, b);
;     }
;     {
;       const int pos = (t < TP) ? (t & 4095) : (PAST + ((t - TP) & 63));
;       const int i = lane & 15;
;       const float x1 = zkr[(size_t)t * 32 + i], x2 = zkr[(size_t)t * 32 + 16 + i];
;       const float2 cs = rt[pos * 16 + i];
;       const float r = (lane < 16) ? (x1 * cs.x - x2 * cs.y) : (x1 * cs.y + x2 * cs.x);
;       if (lane < 32) {
;         float* o = (t < TP) ? p.out + O_EP + (size_t)t * 32 : p.out + O_ES + (size_t)(t - TP) * 32;
;         o[lane] = r; kpea[(size_t)kr * 32 + lane] = f2bf(r);
;       }
;     }
.LBB0_349:
	v_lshl_add_u64 v[46:47], s[96:97], 0, v[32:33]
	global_load_dwordx4 v[64:67], v[46:47], off
	v_lshl_add_u64 v[106:107], s[96:97], 0, v[38:39]
	global_load_dwordx2 v[108:109], v[106:107], off
	s_mov_b32 s0, 0x8000
	v_cmp_gt_u32_e64 s[44:45], s0, v44
	s_mov_b64 s[0:1], exec
	s_and_b64 exec, exec, s[42:43]
	v_lshl_add_u64 v[110:111], s[96:97], 0, v[42:43]
	v_add_co_u32_e32 v110, vcc, 0x19a5e000, v110
	v_and_b32_e32 v116, 0xfff, v44
	v_and_or_b32 v117, v44, 63, v58
	v_addc_co_u32_e32 v111, vcc, 0, v111, vcc
	v_cndmask_b32_e64 v116, v117, v116, s[44:45]
	global_load_dword v112, v[110:111], off
	v_lshl_or_b32 v116, v116, 7, v49
	global_load_dword v113, v[110:111], off offset:64
	s_nop 0
	global_load_dwordx2 v[114:115], v116, s[36:37]
	s_mov_b64 exec, s[0:1]
	s_movk_i32 s0, 0x7fff
	s_waitcnt vmcnt(4)
	v_pk_mul_f32 v[68:69], v[64:65], v[64:65]
	s_nop 0
	v_add_f32_e32 v2, v68, v69
	v_pk_mul_f32 v[46:47], v[66:67], v[66:67]
	s_nop 0
	v_add_f32_e32 v2, v46, v2
	v_add_f32_e32 v2, v47, v2
	ds_bpermute_b32 v25, v29, v2
	s_waitcnt lgkmcnt(0)
	v_add_f32_e32 v2, v2, v25
	ds_bpermute_b32 v25, v31, v2
	s_waitcnt lgkmcnt(0)
	v_add_f32_e32 v2, v2, v25
	ds_bpermute_b32 v25, v59, v2
	s_waitcnt lgkmcnt(0)
	v_add_f32_e32 v2, v2, v25
	ds_bpermute_b32 v25, v60, v2
	s_waitcnt lgkmcnt(0)
	v_add_f32_e32 v2, v2, v25
	ds_bpermute_b32 v25, v61, v2
	s_waitcnt lgkmcnt(0)
	v_add_f32_e32 v2, v2, v25
	ds_bpermute_b32 v25, v62, v2
	s_waitcnt lgkmcnt(0)
	v_add_f32_e32 v2, v2, v25
	v_fmamk_f32 v2, v2, 0x3b800000, v48
	v_cmp_gt_f32_e32 vcc, s26, v2
	v_mul_f32_e32 v25, 0x4b800000, v2
	s_nop 0
	v_cndmask_b32_e32 v2, v2, v25, vcc
	v_rsq_f32_e32 v2, v2
	s_nop 0
	v_mul_f32_e32 v25, 0x45800000, v2
	v_cndmask_b32_e32 v2, v2, v25, vcc
	v_pk_mul_f32 v[46:47], v[64:65], v[2:3] op_sel_hi:[1,0]
	v_pk_mul_f32 v[64:65], v[66:67], v[2:3] op_sel_hi:[1,0]
	v_cmp_lt_u32_e32 vcc, s0, v44
	v_add_u32_e32 v2, 0xffff8000, v44
	v_pk_mul_f32 v[46:47], v[100:101], v[46:47]
	v_pk_mul_f32 v[64:65], v[102:103], v[64:65]
	v_cvt_pk_bf16_f32 v46, v46, v47
	v_cvt_pk_bf16_f32 v47, v64, v65
	v_lshl_add_u64 v[64:65], s[96:97], 0, v[34:35]
	global_store_dwordx2 v[64:65], v[46:47], off
	s_and_saveexec_b64 s[0:1], vcc
	s_xor_b64 s[0:1], exec, s[0:1]
	v_add_u32_e32 v2, 0xffff8000, v44
	v_lshrrev_b32_e32 v2, 6, v2
	s_movk_i32 s2, 0x840
	v_mul_lo_u32 v2, v2, s2
	v_and_or_b32 v2, v44, 63, v2
	v_add_u32_e32 v25, 0xffff8000, v63
	v_add_u32_e32 v2, 0x8800, v2
	v_mov_b64_e32 v[46:47], v[2:3]
	v_mov_b32_e32 v2, v25
	s_andn2_saveexec_b64 s[0:1], s[0:1]
	v_mov_b64_e32 v[46:47], v[44:45]
	s_or_b64 exec, exec, s[0:1]
	v_lshlrev_b64 v[66:67], 9, v[2:3]
	v_lshl_add_u64 v[66:67], s[80:81], 0, v[66:67]
	v_cndmask_b32_e64 v67, v67, v37, s[44:45]
	v_cndmask_b32_e64 v66, v66, v36, s[44:45]
	v_mov_b32_e32 v25, v3
	v_lshl_add_u64 v[66:67], v[66:67], 0, v[24:25]
	s_waitcnt vmcnt(1)
	v_pk_mul_f32 v[68:69], v[108:109], v[108:109]
	s_nop 0
	v_add_f32_e32 v25, v68, v69
	ds_bpermute_b32 v27, v29, v25
	s_waitcnt lgkmcnt(0)
	v_add_f32_e32 v25, v25, v27
	ds_bpermute_b32 v27, v31, v25
	s_waitcnt lgkmcnt(0)
	v_add_f32_e32 v25, v25, v27
	ds_bpermute_b32 v27, v59, v25
	s_waitcnt lgkmcnt(0)
	v_add_f32_e32 v25, v25, v27
	ds_bpermute_b32 v27, v60, v25
	s_waitcnt lgkmcnt(0)
	v_add_f32_e32 v25, v25, v27
	ds_bpermute_b32 v27, v61, v25
	s_waitcnt lgkmcnt(0)
	v_add_f32_e32 v25, v25, v27
	ds_bpermute_b32 v27, v62, v25
	s_waitcnt lgkmcnt(0)
	v_add_f32_e32 v25, v25, v27
	v_fmamk_f32 v25, v25, 0x3c000000, v48
	v_cmp_gt_f32_e32 vcc, s26, v25
	v_mul_f32_e32 v27, 0x4b800000, v25
	s_nop 0
	v_cndmask_b32_e32 v25, v25, v27, vcc
	v_rsq_f32_e32 v25, v25
	s_nop 0
	v_mul_f32_e32 v27, 0x45800000, v25
	v_cndmask_b32_e32 v68, v25, v27, vcc
	v_pk_mul_f32 v[64:65], v[108:109], v[68:69] op_sel_hi:[1,0]
	v_pk_mul_f32 v[64:65], v[104:105], v[64:65]
	global_store_dwordx2 v[66:67], v[64:65], off
	v_cvt_pk_bf16_f32 v25, v64, v65
	v_mad_u64_u32 v[64:65], s[0:1], v46, s86, v[4:5]
	v_mov_b32_e32 v66, v65
	v_mad_u64_u32 v[66:67], s[0:1], v47, s86, v[66:67]
	v_mov_b32_e32 v65, v66
	global_store_dword v[64:65], v25, off
	s_and_saveexec_b64 s[0:1], s[42:43]
	s_cbranch_execz .LBB0_348
	v_lshlrev_b64 v[46:47], 6, v[46:47]
	v_lshl_add_u64 v[46:47], v[6:7], 0, v[46:47]
	v_pk_mul_f32 v[68:69], v[112:113], v[114:115]
	s_nop 0
	v_sub_f32_e32 v25, v68, v69
	v_mov_b32_e32 v68, v113
	v_mov_b32_e32 v69, v112
	v_pk_mul_f32 v[64:65], v[68:69], v[114:115]
	s_nop 0
	v_add_f32_e32 v27, v64, v65
	v_lshlrev_b64 v[64:65], 7, v[2:3]
	v_lshl_add_u64 v[64:65], s[24:25], 0, v[64:65]
	v_cndmask_b32_e64 v25, v27, v25, s[40:41]
	v_cndmask_b32_e64 v65, v65, v41, s[44:45]
	v_cndmask_b32_e64 v64, v64, v40, s[44:45]
	v_mov_b32_e32 v27, v3
	v_lshl_add_u64 v[64:65], v[64:65], 0, v[26:27]
	v_cvt_pk_bf16_f32 v2, v25, s0
	global_store_dword v[64:65], v25, off
	global_store_short v[46:47], v2, off
	s_branch .LBB0_348

; __device__ __forceinline__ f32x16 mfma32(bf16x8 a, bf16x8 b, f32x16 c) { return __builtin_amdgcn_mfma_f32_32x32x16_bf16(a, b, c, 0, 0, 0); }
; __device__ void attn_item_mla(const Params& p, char* lds, int grp, int b, int h, int qblk, int dry) {
;     ...
;         for (int ks = 0; ks < 6; ++ks) {
;           const bf16x8 kf = *(const bf16x8*)(kp0 + sub * 32 * KSTR + ks * 32);
;           S[0] = mfma32(kf, qf[0][ks], S[0]);
;           S[1] = mfma32(kf, qf[1][ks], S[1]);
;         }
; #pragma unroll
;         for (int qs = 0; qs < 2; ++qs) {
;           float mx = S[qs][0];
; #pragma unroll
;           for (int r = 1; r < 16; ++r) mx = fmaxf(mx, S[qs][r]);
;           if (__any(mx > m[qs] + 8.0f)) {
;             mx = fmaxf(mx, __shfl_xor(mx, 32));
;             const float mn = fmaxf(m[qs], mx);
;             const float alpha = __builtin_amdgcn_exp2f(m[qs] - mn);
;             m[qs] = mn; l[qs] *= alpha;
; #pragma unroll
;             for (int i = 0; i < 2; ++i)
; #pragma unroll
;               for (int r = 0; r < 16; ++r) O[qs][i][r] *= alpha;
.LBB0_708:
	s_mul_i32 s0, s16, 0x1a00
	v_add_u32_e32 v10, s0, v15
	ds_read_b128 v[2:5], v10
	ds_read_b128 v[6:9], v10 offset:32
	s_waitcnt lgkmcnt(1)
	v_mfma_f32_32x32x16_bf16 v[96:111], v[2:5], v[112:115], 0
	v_mfma_f32_32x32x16_bf16 v[80:95], v[2:5], v[128:131], 0
	ds_read_b128 v[2:5], v10 offset:64
	s_waitcnt lgkmcnt(1)
	v_mfma_f32_32x32x16_bf16 v[96:111], v[6:9], v[116:119], v[96:111]
	v_mfma_f32_32x32x16_bf16 v[80:95], v[6:9], v[132:135], v[80:95]
	ds_read_b128 v[6:9], v10 offset:96
	s_waitcnt lgkmcnt(1)
	v_mfma_f32_32x32x16_bf16 v[96:111], v[2:5], v[120:123], v[96:111]
	v_mfma_f32_32x32x16_bf16 v[80:95], v[2:5], v[136:139], v[80:95]
	ds_read_b128 v[2:5], v10 offset:128
	s_waitcnt lgkmcnt(1)
	v_mfma_f32_32x32x16_bf16 v[96:111], v[6:9], v[124:127], v[96:111]
	v_mfma_f32_32x32x16_bf16 v[80:95], v[6:9], v[140:143], v[80:95]
	ds_read_b128 v[6:9], v10 offset:160
	s_waitcnt lgkmcnt(1)
	v_mfma_f32_32x32x16_bf16 v[96:111], v[2:5], v[152:155], v[96:111]
	v_mfma_f32_32x32x16_bf16 v[80:95], v[2:5], v[160:163], v[80:95]
	s_waitcnt lgkmcnt(0)
	v_mfma_f32_32x32x16_bf16 v[96:111], v[6:9], v[156:159], v[96:111]
	v_mfma_f32_32x32x16_bf16 v[80:95], v[6:9], v[164:167], v[80:95]
	s_nop 10
	v_max_f32_e32 v2, v97, v97
	v_max_f32_e32 v3, v96, v96
	v_max_f32_e32 v2, v3, v2
	v_max3_f32 v2, v2, v98, v99
	v_max3_f32 v2, v2, v100, v101
	v_max3_f32 v2, v2, v102, v103
	v_max3_f32 v2, v2, v104, v105
	v_max3_f32 v2, v2, v106, v107
	v_max3_f32 v2, v2, v108, v109
	v_max3_f32 v2, v2, v110, v111
	v_add_f32_e32 v3, 0x41000000, v0
	v_cmp_gt_f32_e32 vcc, v2, v3
	s_cbranch_vccz .LBB0_710
	v_and_b32_e32 v4, 64, v234
	v_xor_b32_e32 v3, 32, v234
	v_add_u32_e32 v4, 64, v4
	v_cmp_lt_i32_e32 vcc, v3, v4
	s_nop 1
	v_cndmask_b32_e32 v3, v234, v3, vcc
	v_lshlrev_b32_e32 v3, 2, v3
	ds_bpermute_b32 v3, v3, v2
	s_waitcnt lgkmcnt(0)
	v_max3_f32 v2, v0, v2, v3
	v_sub_f32_e32 v0, v0, v2
	v_exp_f32_e32 v0, v0
	s_nop 0
	v_mul_f32_e32 v14, v14, v0
	v_pk_mul_f32 v[78:79], v[78:79], v[0:1] op_sel_hi:[1,0]
	v_pk_mul_f32 v[76:77], v[76:77], v[0:1] op_sel_hi:[1,0]
	v_pk_mul_f32 v[74:75], v[74:75], v[0:1] op_sel_hi:[1,0]
	v_pk_mul_f32 v[72:73], v[72:73], v[0:1] op_sel_hi:[1,0]
	v_pk_mul_f32 v[70:71], v[70:71], v[0:1] op_sel_hi:[1,0]
	v_pk_mul_f32 v[68:69], v[68:69], v[0:1] op_sel_hi:[1,0]
	v_pk_mul_f32 v[66:67], v[66:67], v[0:1] op_sel_hi:[1,0]
	v_pk_mul_f32 v[64:65], v[64:65], v[0:1] op_sel_hi:[1,0]
	v_pk_mul_f32 v[62:63], v[62:63], v[0:1] op_sel_hi:[1,0]
	v_pk_mul_f32 v[60:61], v[60:61], v[0:1] op_sel_hi:[1,0]
	v_pk_mul_f32 v[58:59], v[58:59], v[0:1] op_sel_hi:[1,0]
	v_pk_mul_f32 v[56:57], v[56:57], v[0:1] op_sel_hi:[1,0]
	v_pk_mul_f32 v[54:55], v[54:55], v[0:1] op_sel_hi:[1,0]
	v_pk_mul_f32 v[52:53], v[52:53], v[0:1] op_sel_hi:[1,0]
	v_pk_mul_f32 v[50:51], v[50:51], v[0:1] op_sel_hi:[1,0]
	v_pk_mul_f32 v[48:49], v[48:49], v[0:1] op_sel_hi:[1,0]
	v_mov_b32_e32 v0, v2

; __global__ void __launch_bounds__(256, 2) mega(Params p, int ph_lo, int ph_hi, int dupmask) {
;     ...
;   RUN_PHASE(11, phase_peer_gather(p, lds))
.LBB0_1161:
	s_cmp_gt_i32 s40, 11
	s_cselect_b64 s[0:1], -1, 0
	s_cmp_lt_i32 s41, 12
	s_cselect_b64 s[2:3], -1, 0
	s_or_b64 s[0:1], s[0:1], s[2:3]
	s_and_b64 vcc, exec, s[0:1]
	s_cbranch_vccnz .LBB0_1248
; __device__ __forceinline__ void peer_token_finish(const Params& p, int t, float (&ov)[16], int lane) {
;   const float* xr = (const float*)(p.ws + D_X1) + (size_t)t * DM + lane * 16; const float* g = p.in[24] + lane * 16;
; __device__ void phase_peer_gather(const Params& p, char* lds) {
;   const int wid = threadIdx.x >> 6, lane = threadIdx.x & 63;
;   const int gw = blockIdx.x * 4 + wid, nw = gridDim.x * 4;
;   const int t_main = (T / nw) * nw;
;   for (int t = gw; t < t_main; t += nw) {
	v_readlane_b32 s0, v248, 0
	v_readlane_b32 s1, v248, 1
	s_load_dword s26, s[0:1], 0xf0
	s_bfe_u32 s95, s42, 0x1000b
	s_add_u32 s0, s0, 0xf0
	s_addc_u32 s1, s1, 0
	v_writelane_b32 v247, s0, 8
	s_waitcnt lgkmcnt(0)
	s_lshl_b32 s27, s26, 2
	v_mov_b32_e32 v81, 0
	v_writelane_b32 v247, s1, 9
	s_abs_i32 s0, s27
	v_cvt_f32_u32_e32 v0, s0
	s_sub_i32 s1, 0, s0
	v_mov_b32_e32 v1, v81
	v_lshlrev_b32_e32 v80, 4, v180
	v_rcp_iflag_f32_e32 v0, v0
	s_waitcnt vmcnt(0)
	v_lshl_add_u32 v120, s72, 2, v185
	v_mbcnt_hi_u32_b32 v128, -1, v221
	v_and_b32_e32 v2, 4, v181
	v_mul_f32_e32 v0, 0x4f7ffffe, v0
	v_cvt_u32_f32_e32 v0, v0
	v_and_b32_e32 v3, 2, v181
	v_and_b32_e32 v4, 1, v181
	v_and_b32_e32 v5, 7, v181
	v_readfirstlane_b32 s2, v0
	s_mul_i32 s1, s1, s2
	s_mul_hi_u32 s1, s2, s1
	s_add_i32 s2, s2, s1
	s_mul_hi_u32 s1, s2, 0x8200
	s_mul_i32 s1, s1, s0
	s_sub_i32 s1, 0x8200, s1
	s_sub_i32 s2, s1, s0
	s_cmp_ge_u32 s1, s0
	s_cselect_b32 s1, s2, s1
	s_sub_i32 s2, s1, s0
	s_cmp_ge_u32 s1, s0
	s_cselect_b32 s0, s2, s1
	s_sub_i32 s29, 0x8200, s0
	s_add_i32 s0, s29, s72
	s_cmp_lt_i32 s0, 0x8200
	v_writelane_b32 v248, s0, 27
	s_cselect_b64 s[0:1], -1, 0
	v_writelane_b32 v247, s0, 50
	v_lshlrev_b32_e32 v0, 5, v180
	s_add_u32 s36, s96, 0x1228e000
	v_writelane_b32 v247, s1, 51
	v_lshl_add_u64 v[0:1], s[96:97], 0, v[0:1]
	s_mov_b64 s[0:1], 0x5b7e000
	s_addc_u32 s37, s97, 0
	v_lshl_add_u64 v[82:83], v[0:1], 0, s[0:1]
	v_lshl_add_u64 v[0:1], s[96:97], 0, v[80:81]
	s_mov_b64 s[0:1], 0x1699e000
	s_add_u32 s16, s96, 0x1899e000
	v_lshl_add_u64 v[84:85], v[0:1], 0, s[0:1]
	s_mov_b64 s[0:1], 0x1699e400
	v_lshlrev_b32_e32 v80, 6, v180
	s_addc_u32 s17, s97, 0
	v_lshl_add_u64 v[86:87], v[0:1], 0, s[0:1]
	v_lshl_add_u64 v[0:1], s[96:97], 0, v[80:81]
	s_mov_b64 s[0:1], 0xa08e000
	s_add_u32 s18, s96, 0x132ce000
	v_lshl_add_u64 v[88:89], v[0:1], 0, s[0:1]
	v_readlane_b32 s0, v248, 2
	s_addc_u32 s19, s97, 0
	v_readlane_b32 s1, v248, 3
	v_readlane_b32 s2, v248, 4
	v_readlane_b32 s3, v248, 5
	v_lshl_add_u64 v[90:91], s[0:1], 0, v[80:81]
	global_load_dwordx4 v[154:157], v[90:91], off
	global_load_dwordx4 v[158:161], v[90:91], off offset:16
	global_load_dwordx4 v[162:165], v[90:91], off offset:32
	global_load_dwordx4 v[166:169], v[90:91], off offset:48
	s_add_u32 s0, s96, 0x166a400
	s_addc_u32 s1, s97, 0
	v_writelane_b32 v248, s0, 35
	v_lshl_add_u64 v[92:93], s[2:3], 0, v[80:81]
	v_lshlrev_b32_e32 v0, 1, v181
	v_writelane_b32 v248, s1, 36
	v_lshlrev_b32_e32 v121, 5, v185
	v_readlane_b32 s2, v248, 8
	s_cmp_eq_u32 s2, 0
	s_cselect_b64 s[0:1], -1, 0
	v_writelane_b32 v248, s0, 33
	v_and_b32_e32 v129, 64, v128
	s_mov_b32 s28, 0
	v_writelane_b32 v248, s1, 34
	s_add_u32 s0, s96, 0x166a500
	s_addc_u32 s1, s97, 0
	v_writelane_b32 v248, s0, 11
	s_cmp_eq_u32 s2, 1
	v_add_u32_e32 v122, 32, v121
	v_writelane_b32 v248, s1, 12
	s_cselect_b64 s[0:1], -1, 0
	v_writelane_b32 v248, s0, 54
	v_lshl_or_b32 v123, v185, 12, v80
	v_lshlrev_b32_e32 v125, 2, v5
	v_writelane_b32 v248, s1, 55
	s_add_u32 s0, s96, 0x166a600
	s_addc_u32 s1, s97, 0
	v_writelane_b32 v248, s0, 0
	s_cmp_eq_u32 s2, 2
	s_mov_b32 s33, 0x10000
	v_writelane_b32 v248, s1, 1
	s_cselect_b64 s[0:1], -1, 0
	s_add_u32 s88, s96, 0x166a700
	s_addc_u32 s89, s97, 0
	v_writelane_b32 v248, s0, 58
	s_cmp_eq_u32 s2, 3
	v_mov_b32_e32 v126, 0x3ba10414
	v_writelane_b32 v248, s1, 59
	s_cselect_b64 s[0:1], -1, 0
	s_add_u32 s86, s96, 0x166a800
	s_addc_u32 s87, s97, 0
	v_writelane_b32 v248, s0, 62
	s_cmp_eq_u32 s2, 4
	v_mov_b32_e32 v127, 0x358637bd
	v_writelane_b32 v248, s1, 63
	s_cselect_b64 s[0:1], -1, 0
	s_add_u32 s84, s96, 0x166a900
	s_addc_u32 s85, s97, 0
	v_writelane_b32 v247, s0, 2
	s_cmp_eq_u32 s2, 5
	v_xor_b32_e32 v130, 1, v128
	v_writelane_b32 v247, s1, 3
	s_cselect_b64 s[0:1], -1, 0
	v_writelane_b32 v247, s0, 6
	v_add_u32_e32 v131, 64, v129
	v_xor_b32_e32 v132, 2, v128
	v_writelane_b32 v247, s1, 7
	s_add_u32 s0, s96, 0x166aa00
	s_addc_u32 s1, s97, 0
	s_cmp_eq_u32 s2, 6
	s_cselect_b64 s[4:5], -1, 0
	v_writelane_b32 v247, s4, 10
	v_xor_b32_e32 v133, 4, v128
	v_xor_b32_e32 v134, 8, v128
	v_writelane_b32 v247, s5, 11
	s_add_u32 s4, s96, 0x166ab00
	s_addc_u32 s5, s97, 0
	s_cmp_eq_u32 s2, 7
	s_cselect_b64 s[6:7], -1, 0
	v_writelane_b32 v247, s6, 14
	v_xor_b32_e32 v135, 16, v128
	v_xor_b32_e32 v136, 32, v128
	v_writelane_b32 v247, s7, 15
	s_add_u32 s6, s96, 0x166ac00
	s_addc_u32 s7, s97, 0
	s_cmp_eq_u32 s2, 8
	s_cselect_b64 s[8:9], -1, 0
	v_writelane_b32 v247, s8, 18
	v_or_b32_e32 v137, v129, v5
	v_mov_b32_e32 v138, 0xb9c68948
	v_writelane_b32 v247, s9, 19
	s_add_u32 s8, s96, 0x166ad00
	s_addc_u32 s9, s97, 0
	s_cmp_eq_u32 s2, 9
	s_cselect_b64 s[10:11], -1, 0
	v_writelane_b32 v247, s10, 22
	v_mov_b32_e32 v139, 0x7f800000
	v_mov_b32_e32 v140, 0x880
	v_writelane_b32 v247, s11, 23
	s_add_u32 s10, s96, 0x166ae00
	s_addc_u32 s11, s97, 0
	s_cmp_eq_u32 s2, 10
	s_cselect_b64 s[12:13], -1, 0
	v_writelane_b32 v247, s12, 26
	v_mov_b32_e32 v94, 0x12300
	v_mov_b32_e32 v96, 0x12304
	v_writelane_b32 v247, s13, 27
	s_add_u32 s12, s96, 0x166af00
	s_addc_u32 s13, s97, 0
	s_cmp_eq_u32 s2, 11
	s_cselect_b64 s[14:15], -1, 0
	v_writelane_b32 v247, s14, 30
	s_mov_b32 s34, 0xbcc618b2
	s_mov_b32 s35, 0x3dda74e4
	v_writelane_b32 v247, s15, 31
	s_add_u32 s14, s96, 0x166b000
	s_addc_u32 s15, s97, 0
	s_cmp_eq_u32 s2, 12
	s_cselect_b64 s[20:21], -1, 0
	v_writelane_b32 v247, s20, 34
	s_mov_b32 s82, 0x3f228afd
	s_mov_b32 s83, 0x3e03c728
	v_writelane_b32 v247, s21, 35
	s_add_u32 s20, s96, 0x166b100
	s_addc_u32 s21, s97, 0
	s_cmp_eq_u32 s2, 13
	s_cselect_b64 s[22:23], -1, 0
	v_writelane_b32 v247, s22, 38
	s_mov_b32 s90, 0xbfb8aa3b
	s_mov_b32 s91, 0x42ce8ed0
	v_writelane_b32 v247, s23, 39
	s_add_u32 s22, s96, 0x166b200
	s_addc_u32 s23, s97, 0
	s_cmp_eq_u32 s2, 14
	s_cselect_b64 s[24:25], -1, 0
	v_writelane_b32 v247, s24, 42
	s_mov_b32 s92, 0xc2b17218
	s_brev_b32 s93, -2
	v_writelane_b32 v247, s25, 43
	s_add_u32 s24, s96, 0x166b300
	s_addc_u32 s25, s97, 0
	s_cmp_eq_u32 s2, 15
	s_cselect_b64 s[30:31], -1, 0
	v_writelane_b32 v247, s30, 46
	s_lshl_b32 s2, s2, 8
	s_mov_b32 s94, 0x800000
	v_writelane_b32 v247, s31, 47
	v_readlane_b32 s30, v248, 6
	v_readlane_b32 s31, v248, 7
	s_add_u32 s2, s30, s2
	s_addc_u32 s3, s31, 0
	s_add_u32 s30, s2, 0x1400
	s_addc_u32 s31, s3, 0
	v_writelane_b32 v248, s30, 60
	s_add_u32 s2, s2, 0x2400
	s_addc_u32 s3, s3, 0
	v_writelane_b32 v248, s31, 61
	v_writelane_b32 v248, s2, 56
	s_mov_b32 s30, 0x378e98ab
	s_mov_b32 s31, 0x3b7cd369
	v_writelane_b32 v248, s3, 57
	s_add_u32 s2, s96, 0x166d400
	s_addc_u32 s3, s97, 0
	v_writelane_b32 v247, s2, 4
	v_cmp_eq_u32_e64 s[38:39], 0, v4
	v_cmp_eq_u32_e64 s[40:41], 0, v3
	v_writelane_b32 v247, s3, 5
	s_add_u32 s2, s96, 0x166d500
	s_addc_u32 s3, s97, 0
	v_writelane_b32 v247, s2, 0
	v_cmp_eq_u32_e64 s[42:43], 0, v2
	v_cmp_gt_u32_e64 s[44:45], 64, v181
	v_writelane_b32 v247, s3, 1
	s_movk_i32 s2, 0x80
	v_and_or_b32 v124, v0, s2, 28
	v_cmp_gt_i32_e64 s[2:3], s29, v120
	v_cmp_lt_u32_e64 s[46:47], 63, v181
	s_nop 0
	v_writelane_b32 v246, s2, 14
	s_nop 1
	v_writelane_b32 v246, s3, 15
	s_branch .LBB0_1166

; __device__ __forceinline__ void peer_token_finish(const Params& p, int t, float (&ov)[16], int lane) {
;   const float* xr = (const float*)(p.ws + D_X1) + (size_t)t * DM + lane * 16; const float* g = p.in[24] + lane * 16;
;   float ss = 0.f;
; #pragma unroll
;   for (int i = 0; i < 4; ++i) { f32x4 a = *(const f32x4*)(xr + i * 4); ov[4 * i] += a[0]; ov[4 * i + 1] += a[1]; ov[4 * i + 2] += a[2]; ov[4 * i + 3] += a[3]; }
; #pragma unroll
;   for (int i = 0; i < 16; ++i) ss += ov[i] * ov[i];
;   ss = wave_sum(ss);
;   const float rs = rsqrtf(ss * (1.f / DM) + EPS);
;   float* y = p.out + O_Y + (size_t)t * DM + lane * 16;
; #pragma unroll
;   for (int i = 0; i < 4; ++i) {
;     f32x4 ga = *(const f32x4*)(g + i * 4); f32x4 o;
;     o[0] = ov[4 * i] * rs * ga[0]; o[1] = ov[4 * i + 1] * rs * ga[1]; o[2] = ov[4 * i + 2] * rs * ga[2]; o[3] = ov[4 * i + 3] * rs * ga[3];
;     *(f32x4*)(y + i * 4) = o;
;   }
.LBB0_1168:
	v_lshlrev_b64 v[20:21], 12, v[64:65]
	v_lshl_add_u64 v[12:13], v[88:89], 0, v[20:21]
	global_load_dwordx4 v[0:3], v[12:13], off
	global_load_dwordx4 v[4:7], v[12:13], off offset:16
	global_load_dwordx4 v[8:11], v[12:13], off offset:32
	s_nop 0
	global_load_dwordx4 v[12:15], v[12:13], off offset:48
	v_lshl_add_u64 v[20:21], v[92:93], 0, v[20:21]
	v_add_u32_e32 v64, s27, v64
	s_waitcnt vmcnt(3)
	v_pk_add_f32 v[0:1], v[116:117], v[0:1]
	v_pk_add_f32 v[2:3], v[118:119], v[2:3]
	v_pk_mul_f32 v[22:23], v[0:1], v[0:1]
	v_pk_mul_f32 v[24:25], v[2:3], v[2:3]
	v_add_f32_e32 v22, v22, v23
	s_waitcnt vmcnt(2)
	v_pk_add_f32 v[4:5], v[112:113], v[4:5]
	v_add_f32_e32 v22, v24, v22
	v_pk_mul_f32 v[26:27], v[4:5], v[4:5]
	v_add_f32_e32 v22, v25, v22
	v_pk_add_f32 v[6:7], v[108:109], v[6:7]
	v_add_f32_e32 v22, v26, v22
	v_pk_mul_f32 v[28:29], v[6:7], v[6:7]
	v_add_f32_e32 v22, v27, v22
	s_waitcnt vmcnt(1)
	v_pk_add_f32 v[8:9], v[114:115], v[8:9]
	v_add_f32_e32 v22, v28, v22
	v_pk_mul_f32 v[30:31], v[8:9], v[8:9]
	v_add_f32_e32 v22, v29, v22
	v_pk_add_f32 v[10:11], v[110:111], v[10:11]
	v_add_f32_e32 v22, v30, v22
	v_pk_mul_f32 v[32:33], v[10:11], v[10:11]
	v_add_f32_e32 v22, v31, v22
	s_waitcnt vmcnt(0)
	v_pk_add_f32 v[12:13], v[106:107], v[12:13]
	v_add_f32_e32 v22, v32, v22
	v_pk_mul_f32 v[34:35], v[12:13], v[12:13]
	v_add_f32_e32 v22, v33, v22
	v_pk_add_f32 v[14:15], v[104:105], v[14:15]
	v_add_f32_e32 v22, v34, v22
	v_pk_mul_f32 v[36:37], v[14:15], v[14:15]
	v_add_f32_e32 v22, v35, v22
	v_add_f32_e32 v22, v36, v22
	v_add_f32_e32 v22, v37, v22
	ds_bpermute_b32 v23, v144, v22
	s_waitcnt lgkmcnt(0)
	v_add_f32_e32 v22, v22, v23
	ds_bpermute_b32 v23, v143, v22
	s_waitcnt lgkmcnt(0)
	v_add_f32_e32 v22, v22, v23
	ds_bpermute_b32 v23, v142, v22
	s_waitcnt lgkmcnt(0)
	v_add_f32_e32 v22, v22, v23
	ds_bpermute_b32 v23, v141, v22
	s_waitcnt lgkmcnt(0)
	v_add_f32_e32 v22, v22, v23
	ds_bpermute_b32 v23, v97, v22
	s_waitcnt lgkmcnt(0)
	v_add_f32_e32 v22, v22, v23
	ds_bpermute_b32 v23, v95, v22
	s_waitcnt lgkmcnt(0)
	v_add_f32_e32 v22, v22, v23
	v_fmamk_f32 v22, v22, 0x3a800000, v127
	v_mul_f32_e32 v23, 0x4b800000, v22
	v_cmp_gt_f32_e32 vcc, s94, v22
	s_nop 1
	v_cndmask_b32_e32 v22, v22, v23, vcc
	v_rsq_f32_e32 v22, v22
	s_nop 0
	v_mul_f32_e32 v23, 0x45800000, v22
	v_cndmask_b32_e32 v22, v22, v23, vcc
	v_pk_mul_f32 v[0:1], v[0:1], v[22:23] op_sel_hi:[1,0]
	v_pk_mul_f32 v[2:3], v[2:3], v[22:23] op_sel_hi:[1,0]
	v_pk_mul_f32 v[4:5], v[4:5], v[22:23] op_sel_hi:[1,0]
	v_pk_mul_f32 v[6:7], v[6:7], v[22:23] op_sel_hi:[1,0]
	v_pk_mul_f32 v[0:1], v[154:155], v[0:1]
	v_pk_mul_f32 v[2:3], v[156:157], v[2:3]
	v_pk_mul_f32 v[8:9], v[8:9], v[22:23] op_sel_hi:[1,0]
	v_pk_mul_f32 v[10:11], v[10:11], v[22:23] op_sel_hi:[1,0]
	global_store_dwordx4 v[20:21], v[0:3], off
	v_pk_mul_f32 v[4:5], v[158:159], v[4:5]
	v_pk_mul_f32 v[6:7], v[160:161], v[6:7]
	v_pk_mul_f32 v[12:13], v[12:13], v[22:23] op_sel_hi:[1,0]
	v_pk_mul_f32 v[14:15], v[14:15], v[22:23] op_sel_hi:[1,0]
	global_store_dwordx4 v[20:21], v[4:7], off offset:16
	v_pk_mul_f32 v[8:9], v[162:163], v[8:9]
	v_pk_mul_f32 v[10:11], v[164:165], v[10:11]
	v_cmp_le_i32_e32 vcc, s29, v64
	s_or_b64 s[50:51], vcc, s[50:51]
	global_store_dwordx4 v[20:21], v[8:11], off offset:32
	v_pk_mul_f32 v[12:13], v[166:167], v[12:13]
	v_pk_mul_f32 v[14:15], v[168:169], v[14:15]
	s_nop 0
	global_store_dwordx4 v[20:21], v[12:15], off offset:48
	s_andn2_b64 exec, exec, s[50:51]
	s_cbranch_execz .LBB0_1175
